# gla_sample item loop: kernarg pointers hoisted to preheader, 4 state quads issued together before the first barrier (one HBM latency instead of four), epilogue operands preloaded
# speedup vs baseline: 1.0473x; 1.0096x over previous
.LBB0_1636:
	v_mov_b32_e32 v130, v0
	s_nop 0
	v_readfirstlane_b32 s2, v130
	s_ashr_i32 s3, s2, 6
	s_sub_i32 s2, s40, 64
	s_cmpk_gt_i32 s40, 0xcf
	s_cselect_b32 s2, s2, -1
	s_cmpk_lt_i32 s40, 0x90
	s_cselect_b32 s2, s40, s2
	s_cmp_lt_i32 s2, 0
	v_and_b32_e32 v132, 63, v130
	s_cbranch_scc1 .LBB0_1657
	s_cmpk_gt_u32 s2, 0x1ff
	s_cbranch_scc1 .LBB0_1656
	s_and_b32 s4, s2, 3
	s_lshl_b32 s5, s4, 7
	v_ashrrev_i32_e32 v4, 5, v130
	s_add_i32 s12, s5, 0x718
	s_lshl_b32 s18, s4, 6
	s_add_i32 s16, s5, 0x928
	v_readlane_b32 s8, v228, 4
	v_lshl_add_u32 v26, v4, 2, s96
	v_add_u32_e32 v4, 0x200, v130
	v_readlane_b32 s9, v228, 5
	s_add_u32 s5, s8, 0x83c0000
	v_ashrrev_i32_e32 v5, 31, v4
	s_addc_u32 s26, s9, 0
	v_ashrrev_i32_e32 v6, 5, v4
	v_lshlrev_b64 v[20:21], 2, v[4:5]
	v_lshlrev_b32_e32 v30, 4, v4
	v_add_u32_e32 v4, 0x400, v130
	s_lshl_b32 s17, s3, 2
	s_waitcnt lgkmcnt(0)
	v_lshlrev_b32_e32 v3, 4, v130
	v_ashrrev_i32_e32 v5, 31, v4
	s_add_i32 s27, s96, s17
	v_add_u32_e32 v14, s16, v130
	s_lshl_b32 s16, s4, 8
	v_add_u32_e32 v2, s96, v3
	v_and_b32_e32 v3, 0x1f0, v3
	v_lshl_add_u32 v27, v6, 2, s96
	v_ashrrev_i32_e32 v6, 5, v4
	v_lshlrev_b64 v[22:23], 2, v[4:5]
	v_lshlrev_b32_e32 v31, 4, v4
	v_add_u32_e32 v4, 0x600, v130
	s_add_u32 s16, s38, s16
	v_ashrrev_i32_e32 v131, 31, v130
	v_add_u32_e32 v3, s96, v3
	v_lshl_add_u32 v28, v6, 2, s96
	v_ashrrev_i32_e32 v6, 5, v4
	v_ashrrev_i32_e32 v5, 31, v4
	v_add_u32_e32 v8, s18, v130
	s_addc_u32 s17, s39, 0
	v_lshlrev_b64 v[18:19], 2, v[130:131]
	v_lshlrev_b64 v[24:25], 2, v[4:5]
	v_lshlrev_b32_e32 v32, 4, v4
	v_lshl_add_u32 v29, v6, 2, s96
	s_movk_i32 s8, 0x80
	s_movk_i32 s10, 0xc0
	v_add_u32_e32 v4, s12, v130
	v_mad_u64_u32 v[6:7], s[12:13], v130, -12, v[2:3]
	v_add_u32_e32 v10, 0x518, v8
	v_add_u32_e32 v12, 0x618, v8
	v_lshl_add_u64 v[16:17], v[130:131], 1, s[16:17]
	s_mov_b64 s[16:17], 0xdc00400
	v_and_b32_e32 v35, 64, v1
	s_mov_b32 s19, 0
	v_cmp_lt_i32_e64 s[6:7], 63, v130
	v_cmp_gt_i32_e64 s[8:9], s8, v130
	v_cmp_gt_u32_e64 s[10:11], s10, v130
	v_subrev_u32_e32 v4, 64, v4
	v_mov_b32_e32 v5, 0
	v_ashrrev_i32_e32 v9, 31, v8
	v_ashrrev_i32_e32 v11, 31, v10
	v_ashrrev_i32_e32 v13, 31, v12
	v_cmp_eq_u32_e64 s[12:13], 0, v130
	v_cmp_eq_u32_e64 s[14:15], 0, v132
	v_ashrrev_i32_e32 v15, 31, v14
	v_lshl_add_u64 v[16:17], v[16:17], 0, s[16:17]
	s_add_i32 s28, s96, 0x8000
	s_movk_i32 s29, 0x3000
	s_lshl_b32 s20, s18, 2
	s_movk_i32 s30, 0x2000
	s_movk_i32 s31, 0x1000
	s_mov_b32 s33, 0xbfb8aa3b
	s_mov_b32 s34, 0x800000
	s_mov_b32 s35, 0x3f317217
	s_mov_b32 s36, 0x7f800000
	v_lshlrev_b64 v[18:19], 2, v[18:19]
	v_lshlrev_b64 v[20:21], 2, v[20:21]
	v_add_u32_e32 v7, s96, v30
	v_lshlrev_b64 v[22:23], 2, v[22:23]
	v_add_u32_e32 v30, s96, v31
	v_lshlrev_b64 v[24:25], 2, v[24:25]
	v_add_u32_e32 v31, s96, v32
	s_add_i32 s37, s96, 0x8504
	v_mov_b32_e32 v32, 0x358637bd
	s_mov_b32 s41, 0xf800000
	v_mov_b32_e32 v33, 0x260
	s_movk_i32 s44, 0x7fff
	v_mov_b32_e32 v34, 0x41b17218
	v_add_u32_e32 v35, 64, v35
	v_xor_b32_e32 v36, 1, v1
	v_xor_b32_e32 v37, 2, v1
	v_xor_b32_e32 v38, 4, v1
	v_xor_b32_e32 v39, 8, v1
	v_xor_b32_e32 v40, 16, v1
	v_mov_b64_e32 v[42:43], s[0:1]
	global_load_dwordx2 v[230:231], v[42:43], off offset:56
	global_load_dwordx2 v[232:233], v[42:43], off offset:152
	global_load_dwordx2 v[250:251], v[42:43], off offset:160
	global_load_dwordx2 v[252:253], v[42:43], off offset:168
	s_waitcnt vmcnt(0)
	s_branch .LBB0_1640

.LBB0_1640:
	s_lshr_b32 s16, s2, 2
	s_add_i32 s18, s16, 0x4000
	s_mul_i32 s17, s18, 0x3000
	s_mul_hi_u32 s16, s18, 0x3000
	s_add_u32 s22, s46, s17
	s_addc_u32 s23, s47, s16
	s_and_b32 s98, s2, 0x7ffffffc
	s_mov_b32 s99, s19
	s_or_b32 s98, s4, s98
	s_lshl_b64 s[98:99], s[98:99], 15
	v_lshl_add_u64 v[246:247], v[230:231], 0, s[98:99]
	v_lshl_add_u64 v[234:235], v[246:247], 0, v[18:19]
	v_lshl_add_u64 v[238:239], v[246:247], 0, v[20:21]
	v_lshl_add_u64 v[242:243], v[246:247], 0, v[22:23]
	v_lshl_add_u64 v[246:247], v[246:247], 0, v[24:25]
	s_and_saveexec_b64 s[16:17], s[6:7]
	s_cbranch_execz .Lmy_gs0_nold
	global_load_dwordx4 v[234:237], v[234:235], off
	global_load_dwordx4 v[238:241], v[238:239], off
	global_load_dwordx4 v[242:245], v[242:243], off
	global_load_dwordx4 v[246:249], v[246:247], off
.Lmy_gs0_nold:
	s_or_b64 exec, exec, s[16:17]
	s_barrier
	s_and_saveexec_b64 s[16:17], s[6:7]
	s_xor_b64 s[16:17], exec, s[16:17]
	s_cbranch_execz .LBB0_1644
	s_and_saveexec_b64 s[24:25], s[10:11]
	s_cbranch_execz .LBB0_1643
	v_lshl_add_u64 v[42:43], v[4:5], 2, s[22:23]
	global_load_dword v41, v[42:43], off
	s_waitcnt vmcnt(0) lgkmcnt(0)
	ds_write_b32 v6, v41 offset:33280

.LBB0_1644:
	s_andn2_saveexec_b64 s[24:25], s[16:17]
	s_cbranch_execz .LBB0_1648
	v_mov_b32_e32 v41, s22
	s_mov_b32 s21, s19
	v_mov_b32_e32 v46, s23
	v_add_co_u32_e32 v54, vcc, 0x2000, v41
	v_lshl_add_u64 v[42:43], v[10:11], 2, s[22:23]
	v_lshl_add_u64 v[44:45], v[12:13], 2, s[22:23]
	v_addc_co_u32_e32 v55, vcc, 0, v46, vcc
	global_load_dword v41, v[42:43], off
	global_load_dword v66, v[44:45], off
	s_nop 0
	global_load_dwordx4 v[42:45], v[54:55], off offset:1120
	global_load_dwordx4 v[46:49], v[54:55], off offset:1136
	global_load_dwordx4 v[50:53], v[54:55], off offset:1152
	s_nop 0
	global_load_dwordx4 v[54:57], v[54:55], off offset:1168
	v_xor_b32_e32 v80, 32, v1
	s_waitcnt lgkmcnt(0)
	v_lshl_add_u64 v[58:59], v[232:233], 0, s[20:21]
	v_lshl_add_u64 v[60:61], v[8:9], 2, v[250:251]
	v_lshl_add_u64 v[58:59], v[130:131], 2, v[58:59]
	global_load_dword v67, v[60:61], off
	global_load_dword v68, v[58:59], off
	global_load_dword v69, v[58:59], off offset:1024
	global_load_dword v70, v[58:59], off offset:2048
	global_load_dword v71, v[58:59], off offset:3072
	v_add_co_u32_e64 v62, s[16:17], s30, v58
	v_add_co_u32_e32 v60, vcc, s31, v58
	s_nop 0
	v_addc_co_u32_e64 v63, s[16:17], 0, v59, s[16:17]
	v_add_co_u32_e64 v64, s[16:17], s29, v58
	v_addc_co_u32_e32 v61, vcc, 0, v59, vcc
	s_nop 0
	v_addc_co_u32_e64 v65, s[16:17], 0, v59, s[16:17]
	global_load_dword v58, v[62:63], off offset:-4096
	global_load_dword v59, v[60:61], off offset:1024
	global_load_dword v72, v[60:61], off offset:2048
	s_nop 0
	global_load_dword v60, v[60:61], off offset:3072
	s_nop 0
	global_load_dword v61, v[62:63], off
	global_load_dword v73, v[62:63], off offset:1024
	global_load_dword v74, v[62:63], off offset:2048
	s_nop 0
	global_load_dword v62, v[62:63], off offset:3072
	s_nop 0
	global_load_dword v63, v[64:65], off
	global_load_dword v75, v[64:65], off offset:1024
	global_load_dword v76, v[64:65], off offset:2048
	s_nop 0
	global_load_dword v64, v[64:65], off offset:3072
	global_load_dwordx4 v[234:237], v[234:235], off
	global_load_dwordx4 v[238:241], v[238:239], off
	global_load_dwordx4 v[242:245], v[242:243], off
	global_load_dwordx4 v[246:249], v[246:247], off
	v_cmp_lt_i32_e32 vcc, v36, v35
	s_waitcnt vmcnt(4)
	v_mul_f32_e32 v77, 0x3e000000, v41
	v_mul_f32_e32 v41, v77, v66
	v_cndmask_b32_e32 v65, v1, v36, vcc
	v_lshlrev_b32_e32 v65, 2, v65
	ds_bpermute_b32 v41, v65, v41
	v_cmp_lt_i32_e32 vcc, v37, v35
	s_waitcnt lgkmcnt(0)
	v_fmac_f32_e32 v41, v77, v66
	v_cndmask_b32_e32 v65, v1, v37, vcc
	v_lshlrev_b32_e32 v65, 2, v65
	ds_bpermute_b32 v65, v65, v41
	v_cmp_lt_i32_e32 vcc, v38, v35
	s_waitcnt lgkmcnt(0)
	v_add_f32_e32 v41, v41, v65
	v_cndmask_b32_e32 v78, v1, v38, vcc
	v_cmp_lt_i32_e32 vcc, v39, v35
	v_lshlrev_b32_e32 v78, 2, v78
	ds_bpermute_b32 v65, v78, v41
	v_cndmask_b32_e32 v79, v1, v39, vcc
	v_cmp_lt_i32_e32 vcc, v40, v35
	v_lshlrev_b32_e32 v79, 2, v79
	s_waitcnt lgkmcnt(0)
	v_add_f32_e32 v41, v41, v65
	v_cndmask_b32_e32 v78, v1, v40, vcc
	v_cmp_lt_i32_e32 vcc, v80, v35
	ds_bpermute_b32 v65, v79, v41
	v_lshlrev_b32_e32 v78, 2, v78
	s_waitcnt lgkmcnt(0)
	v_add_f32_e32 v41, v41, v65
	v_fmac_f32_e32 v67, v42, v68
	v_fmac_f32_e32 v67, v43, v69
	v_fmac_f32_e32 v67, v44, v70
	v_fmac_f32_e32 v67, v45, v71
	v_cndmask_b32_e32 v43, v1, v80, vcc
	v_fmac_f32_e32 v67, v46, v58
	v_fmac_f32_e32 v67, v47, v59
	v_fmac_f32_e32 v67, v48, v72
	v_fmac_f32_e32 v67, v49, v60
	v_fmac_f32_e32 v67, v50, v61
	v_fmac_f32_e32 v67, v51, v73
	v_fmac_f32_e32 v67, v52, v74
	v_fmac_f32_e32 v67, v53, v62
	v_fmac_f32_e32 v67, v54, v63
	v_fmac_f32_e32 v67, v55, v75
	v_fmac_f32_e32 v67, v56, v76
	v_fmac_f32_e32 v67, v57, v64
	v_mul_f32_e64 v42, |v67|, s33
	v_exp_f32_e32 v42, v42
	v_min_f32_e32 v45, 0, v67
	v_lshlrev_b32_e32 v43, 2, v43
	v_add_f32_e32 v42, 1.0, v42
	v_cmp_gt_f32_e32 vcc, s34, v42
	s_nop 1
	v_cndmask_b32_e64 v44, 0, 32, vcc
	v_ldexp_f32 v42, v42, v44
	v_log_f32_e32 v42, v42
	ds_bpermute_b32 v44, v78, v41
	v_cndmask_b32_e32 v46, 0, v34, vcc
	v_mul_f32_e32 v47, 0x3f317217, v42
	v_fma_f32 v47, v42, s35, -v47
	v_fmac_f32_e32 v47, 0x3377d1cf, v42
	v_fmac_f32_e32 v47, 0x3f317217, v42
	v_cmp_lt_f32_e64 vcc, |v42|, s36
	s_waitcnt lgkmcnt(0)
	v_add_f32_e32 v41, v41, v44
	v_cndmask_b32_e32 v42, v42, v47, vcc
	v_sub_f32_e32 v42, v42, v46
	v_sub_f32_e32 v42, v45, v42
	v_mul_f32_e32 v42, 0x3d800000, v42
	v_mul_f32_e32 v42, 0x3fb8aa3b, v42
	v_exp_f32_e32 v45, v42
	ds_bpermute_b32 v42, v43, v41
	v_mul_f32_e32 v43, v77, v45
	ds_write2st64_b32 v6, v43, v66 offset0:128 offset1:129
	ds_write_b32 v6, v45 offset:33280
	s_and_saveexec_b64 s[16:17], s[12:13]
	s_cbranch_execz .LBB0_1647
	s_waitcnt lgkmcnt(2)
	v_add_f32_e32 v41, v41, v42
	v_mov_b32_e32 v42, s96
	ds_write_b32 v42, v41 offset:34048

.LBB0_1648:
	s_or_b64 exec, exec, s[24:25]
	s_waitcnt lgkmcnt(0)
	v_mov_b64_e32 v[42:43], s[0:1]
	s_waitcnt lgkmcnt(0)
	s_barrier
	s_and_b32 s16, s2, 0x7ffffffc
	s_mov_b32 s17, s19
	s_or_b32 s16, s4, s16
	s_lshl_b64 s[16:17], s[16:17], 15
	s_add_u32 s16, s5, s16
	s_addc_u32 s17, s26, s17
	v_mov_b32_e32 v41, 0
	v_lshl_add_u64 v[54:55], s[16:17], 0, v[18:19]
	v_lshl_add_u64 v[62:63], s[16:17], 0, v[20:21]
	v_lshl_add_u64 v[64:65], s[16:17], 0, v[22:23]
	v_lshl_add_u64 v[66:67], s[16:17], 0, v[24:25]
	ds_read_b128 v[46:49], v3 offset:33536
	ds_read2st64_b32 v[52:53], v26 offset0:129 offset1:130
	ds_read2st64_b32 v[56:57], v27 offset0:129 offset1:130
	ds_read2st64_b32 v[58:59], v28 offset0:129 offset1:130
	ds_read2st64_b32 v[60:61], v29 offset0:129 offset1:130
	s_waitcnt vmcnt(0)
	ds_write_b128 v2, v[234:237]
	ds_write_b128 v7, v[238:241]
	ds_write_b128 v30, v[242:245]
	ds_write_b128 v31, v[246:249]
	s_waitcnt lgkmcnt(4)
	v_pk_mul_f32 v[44:45], v[48:49], v[52:53] op_sel_hi:[1,0]
	v_pk_mul_f32 v[42:43], v[46:47], v[52:53] op_sel_hi:[1,0]
	v_mov_b32_e32 v52, v53
	v_pk_fma_f32 v[236:237], v[236:237], v[52:53], v[44:45] op_sel_hi:[1,0,1]
	v_pk_fma_f32 v[234:235], v[234:235], v[52:53], v[42:43] op_sel_hi:[1,0,1]
	global_store_dwordx4 v[54:55], v[234:237], off
	v_pk_mul_f32 v[44:45], v[48:49], v[56:57] op_sel_hi:[1,0]
	v_pk_mul_f32 v[42:43], v[46:47], v[56:57] op_sel_hi:[1,0]
	v_mov_b32_e32 v56, v57
	v_pk_fma_f32 v[240:241], v[240:241], v[56:57], v[44:45] op_sel_hi:[1,0,1]
	v_pk_fma_f32 v[238:239], v[238:239], v[56:57], v[42:43] op_sel_hi:[1,0,1]
	global_store_dwordx4 v[62:63], v[238:241], off
	v_pk_mul_f32 v[44:45], v[48:49], v[58:59] op_sel_hi:[1,0]
	v_pk_mul_f32 v[42:43], v[46:47], v[58:59] op_sel_hi:[1,0]
	v_mov_b32_e32 v58, v59
	v_pk_fma_f32 v[244:245], v[244:245], v[58:59], v[44:45] op_sel_hi:[1,0,1]
	v_pk_fma_f32 v[242:243], v[242:243], v[58:59], v[42:43] op_sel_hi:[1,0,1]
	global_store_dwordx4 v[64:65], v[242:245], off
	v_pk_mul_f32 v[44:45], v[48:49], v[60:61] op_sel_hi:[1,0]
	v_pk_mul_f32 v[42:43], v[46:47], v[60:61] op_sel_hi:[1,0]
	v_mov_b32_e32 v60, v61
	v_pk_fma_f32 v[248:249], v[248:249], v[60:61], v[44:45] op_sel_hi:[1,0,1]
	v_pk_fma_f32 v[246:247], v[246:247], v[60:61], v[42:43] op_sel_hi:[1,0,1]
	global_store_dwordx4 v[66:67], v[246:249], off
	s_waitcnt lgkmcnt(0)
	s_barrier
	s_and_saveexec_b64 s[16:17], s[8:9]
	s_cbranch_execz .LBB0_1654
	v_lshl_add_u64 v[44:45], v[14:15], 2, s[22:23]
	global_load_dword v234, v[44:45], off
	v_lshl_add_u64 v[44:45], v[130:131], 2, v[252:253]
	global_load_dword v235, v[44:45], off
	v_mov_b32_e32 v41, 0
	s_mov_b32 s21, 0
	s_mov_b32 s24, s28

.LBB0_1654:
	s_or_b64 exec, exec, s[16:17]
	s_waitcnt lgkmcnt(0)
	s_barrier
	s_and_saveexec_b64 s[24:25], s[8:9]
	s_cbranch_execz .LBB0_1639
	v_mov_b32_e32 v42, s37
	ds_read2_b32 v[42:43], v42 offset1:1
	s_waitcnt lgkmcnt(0)
	v_add_f32_e32 v42, v42, v43
	v_fmamk_f32 v42, v42, 0x3c000000, v32
	v_mul_f32_e32 v43, 0x4f800000, v42
	v_cmp_gt_f32_e32 vcc, s41, v42
	v_cndmask_b32_e32 v42, v42, v43, vcc
	v_sqrt_f32_e32 v43, v42
	s_nop 0
	v_add_u32_e32 v45, -1, v43
	v_add_u32_e32 v47, 1, v43
	v_fma_f32 v48, -v45, v43, v42
	v_fma_f32 v49, -v47, v43, v42
	v_cmp_ge_f32_e64 s[16:17], 0, v48
	s_nop 1
	v_cndmask_b32_e64 v43, v43, v45, s[16:17]
	v_cmp_lt_f32_e64 s[16:17], 0, v49
	s_nop 1
	v_cndmask_b32_e64 v43, v43, v47, s[16:17]
	v_mul_f32_e32 v45, 0x37800000, v43
	v_cndmask_b32_e32 v43, v43, v45, vcc
	v_cmp_class_f32_e32 vcc, v42, v33
	s_nop 1
	v_cndmask_b32_e32 v42, v43, v42, vcc
	v_div_scale_f32 v43, s[16:17], v42, v42, 1.0
	v_rcp_f32_e32 v45, v43
	v_div_scale_f32 v47, vcc, 1.0, v42, 1.0
	s_lshl_b64 s[16:17], s[18:19], 11
	v_fma_f32 v48, -v43, v45, 1.0
	v_fmac_f32_e32 v45, v48, v45
	v_mul_f32_e32 v48, v47, v45
	v_fma_f32 v49, -v43, v48, v47
	v_fmac_f32_e32 v48, v49, v45
	v_fma_f32 v43, -v43, v48, v47
	s_waitcnt vmcnt(0)
	v_mov_b32_e32 v46, v234
	v_mov_b32_e32 v44, v235
	v_mul_f32_e32 v47, 0xbfb8aa3b, v46
	v_exp_f32_e32 v47, v47
	v_div_fmas_f32 v43, v43, v45, v48
	v_div_fixup_f32 v42, v43, v42, 1.0
	v_mul_f32_e32 v41, v41, v42
	v_add_f32_e32 v43, 1.0, v47
	v_div_scale_f32 v45, s[22:23], v43, v43, v46
	v_rcp_f32_e32 v47, v45
	v_div_scale_f32 v42, vcc, v46, v43, v46
	v_fma_f32 v48, -v45, v47, 1.0
	v_fmac_f32_e32 v47, v48, v47
	v_mul_f32_e32 v48, v42, v47
	v_fma_f32 v49, -v45, v48, v42
	v_fmac_f32_e32 v48, v49, v47
	v_fma_f32 v42, -v45, v48, v42
	v_div_fmas_f32 v42, v42, v47, v48
	v_div_fixup_f32 v42, v42, v43, v46
	v_mul_f32_e32 v41, v44, v41
	v_mul_f32_e32 v41, v41, v42
	v_bfe_u32 v42, v41, 16, 1
	v_add3_u32 v41, v41, v42, s44
	v_lshl_add_u64 v[42:43], v[16:17], 0, s[16:17]
	global_store_short_d16_hi v[42:43], v41, off
	s_branch .LBB0_1639

.LBB0_4243:
	v_mov_b32_e32 v130, v0
	s_nop 0
	v_readfirstlane_b32 s2, v130
	s_ashr_i32 s96, s2, 6
	s_sub_i32 s2, s40, 64
	s_cmpk_gt_i32 s40, 0xcf
	s_cselect_b32 s2, s2, -1
	s_cmpk_lt_i32 s40, 0x90
	s_cselect_b32 s2, s40, s2
	s_cmp_lt_i32 s2, 0
	v_and_b32_e32 v132, 63, v130
	s_cbranch_scc1 .LBB0_4264
	s_cmpk_gt_u32 s2, 0x1ff
	s_cbranch_scc1 .LBB0_4263
	v_ashrrev_i32_e32 v4, 5, v130
	s_and_b32 s16, s2, 3
	v_lshl_add_u32 v26, v4, 2, s94
	v_add_u32_e32 v4, 0x200, v130
	s_lshl_b32 s3, s16, 7
	v_ashrrev_i32_e32 v5, 31, v4
	s_add_i32 s12, s3, 0x718
	s_lshl_b32 s18, s16, 6
	s_add_i32 s17, s3, 0x928
	s_or_b32 s3, s16, 0x200
	v_readlane_b32 s4, v228, 15
	v_ashrrev_i32_e32 v6, 5, v4
	v_lshlrev_b64 v[20:21], 2, v[4:5]
	v_lshlrev_b32_e32 v30, 4, v4
	v_add_u32_e32 v4, 0x400, v130
	v_readlane_b32 s5, v228, 16
	s_add_u32 s4, s4, 0x83c0000
	s_waitcnt lgkmcnt(0)
	v_lshlrev_b32_e32 v3, 4, v130
	v_ashrrev_i32_e32 v5, 31, v4
	s_addc_u32 s5, s5, 0
	v_add_u32_e32 v2, s94, v3
	v_and_b32_e32 v3, 0x1f0, v3
	v_lshl_add_u32 v27, v6, 2, s94
	v_ashrrev_i32_e32 v6, 5, v4
	v_lshlrev_b64 v[22:23], 2, v[4:5]
	v_lshlrev_b32_e32 v31, 4, v4
	v_add_u32_e32 v4, 0x600, v130
	s_lshl_b32 s20, s96, 2
	v_add_u32_e32 v3, s94, v3
	v_lshl_add_u32 v28, v6, 2, s94
	v_ashrrev_i32_e32 v6, 5, v4
	v_ashrrev_i32_e32 v5, 31, v4
	s_add_i32 s26, s94, s20
	s_lshl_b32 s16, s16, 8
	v_lshlrev_b64 v[24:25], 2, v[4:5]
	v_lshlrev_b32_e32 v32, 4, v4
	v_lshl_add_u32 v29, v6, 2, s94
	v_add_u32_e32 v4, s12, v130
	v_mad_u64_u32 v[6:7], s[12:13], v130, -12, v[2:3]
	s_add_u32 s16, s38, s16
	v_ashrrev_i32_e32 v131, 31, v130
	v_add_u32_e32 v7, s18, v130
	v_add_u32_e32 v12, s17, v130
	s_addc_u32 s17, s39, 0
	s_mov_b32 s19, 0
	v_lshlrev_b64 v[18:19], 2, v[130:131]
	s_movk_i32 s8, 0x80
	s_movk_i32 s10, 0xc0
	v_add_u32_e32 v8, 0x518, v7
	v_add_u32_e32 v10, 0x618, v7
	v_lshl_add_u64 v[14:15], v[130:131], 1, s[16:17]
	s_mov_b64 s[16:17], 0xdc00400
	v_and_b32_e32 v35, 64, v1
	v_cmp_lt_i32_e64 s[6:7], 63, v130
	v_cmp_gt_i32_e64 s[8:9], s8, v130
	v_cmp_gt_u32_e64 s[10:11], s10, v130
	v_subrev_u32_e32 v4, 64, v4
	v_mov_b32_e32 v5, 0
	v_ashrrev_i32_e32 v9, 31, v8
	v_ashrrev_i32_e32 v11, 31, v10
	v_cmp_eq_u32_e64 s[12:13], 0, v130
	v_cmp_eq_u32_e64 s[14:15], 0, v132
	v_ashrrev_i32_e32 v13, 31, v12
	v_lshl_add_u64 v[14:15], v[14:15], 0, s[16:17]
	v_lshl_add_u64 v[16:17], s[18:19], 0, v[130:131]
	s_add_i32 s27, s94, 0x8000
	s_movk_i32 s28, 0x4000
	s_lshl_b32 s20, s18, 2
	s_movk_i32 s29, 0x5000
	s_movk_i32 s30, 0x6000
	s_movk_i32 s31, 0x7000
	s_mov_b32 s33, 0xbfb8aa3b
	s_mov_b32 s34, 0x800000
	s_mov_b32 s35, 0x3f317217
	s_mov_b32 s36, 0x7f800000
	v_lshlrev_b64 v[18:19], 2, v[18:19]
	v_lshlrev_b64 v[20:21], 2, v[20:21]
	v_add_u32_e32 v7, s94, v30
	v_lshlrev_b64 v[22:23], 2, v[22:23]
	v_add_u32_e32 v30, s94, v31
	v_lshlrev_b64 v[24:25], 2, v[24:25]
	v_add_u32_e32 v31, s94, v32
	s_add_i32 s37, s94, 0x8504
	v_mov_b32_e32 v32, 0x358637bd
	s_mov_b32 s41, 0xf800000
	v_mov_b32_e32 v33, 0x260
	s_movk_i32 s42, 0x7fff
	v_mov_b32_e32 v34, 0x41b17218
	v_add_u32_e32 v35, 64, v35
	v_xor_b32_e32 v36, 1, v1
	v_xor_b32_e32 v37, 2, v1
	v_xor_b32_e32 v38, 4, v1
	v_xor_b32_e32 v39, 8, v1
	v_xor_b32_e32 v40, 16, v1
	v_xor_b32_e32 v41, 32, v1
	v_mov_b64_e32 v[42:43], s[0:1]
	global_load_dwordx2 v[230:231], v[42:43], off offset:56
	global_load_dwordx2 v[232:233], v[42:43], off offset:152
	global_load_dwordx2 v[250:251], v[42:43], off offset:160
	global_load_dwordx2 v[252:253], v[42:43], off offset:168
	s_waitcnt vmcnt(0)
	s_branch .LBB0_4247

.LBB0_4247:
	s_lshr_b32 s16, s2, 2
	s_add_i32 s18, s16, 0x4000
	s_mul_i32 s17, s18, 0x3000
	s_mul_hi_u32 s16, s18, 0x3000
	s_add_u32 s22, s46, s17
	s_addc_u32 s23, s47, s16
	s_and_b32 s98, s2, 0x7ffffffc
	s_mov_b32 s99, s19
	s_add_i32 s98, s3, s98
	s_lshl_b64 s[98:99], s[98:99], 15
	v_lshl_add_u64 v[246:247], v[230:231], 0, s[98:99]
	v_lshl_add_u64 v[234:235], v[246:247], 0, v[18:19]
	v_lshl_add_u64 v[238:239], v[246:247], 0, v[20:21]
	v_lshl_add_u64 v[242:243], v[246:247], 0, v[22:23]
	v_lshl_add_u64 v[246:247], v[246:247], 0, v[24:25]
	s_and_saveexec_b64 s[16:17], s[6:7]
	s_cbranch_execz .Lmy_gs1_nold
	global_load_dwordx4 v[234:237], v[234:235], off
	global_load_dwordx4 v[238:241], v[238:239], off
	global_load_dwordx4 v[242:245], v[242:243], off
	global_load_dwordx4 v[246:249], v[246:247], off
.Lmy_gs1_nold:
	s_or_b64 exec, exec, s[16:17]
	s_barrier
	s_and_saveexec_b64 s[16:17], s[6:7]
	s_xor_b64 s[16:17], exec, s[16:17]
	s_cbranch_execz .LBB0_4251
	s_and_saveexec_b64 s[24:25], s[10:11]
	s_cbranch_execz .LBB0_4250
	v_lshl_add_u64 v[42:43], v[4:5], 2, s[22:23]
	global_load_dword v42, v[42:43], off
	s_waitcnt vmcnt(0) lgkmcnt(0)
	ds_write_b32 v6, v42 offset:33280

.LBB0_4251:
	s_andn2_saveexec_b64 s[24:25], s[16:17]
	s_cbranch_execz .LBB0_4255
	v_mov_b32_e32 v46, s22
	v_mov_b32_e32 v47, s23
	v_add_co_u32_e32 v54, vcc, 0x2000, v46
	v_lshl_add_u64 v[42:43], v[8:9], 2, s[22:23]
	v_lshl_add_u64 v[44:45], v[10:11], 2, s[22:23]
	v_addc_co_u32_e32 v55, vcc, 0, v47, vcc
	global_load_dword v66, v[42:43], off
	global_load_dword v67, v[44:45], off
	s_nop 0
	global_load_dwordx4 v[42:45], v[54:55], off offset:1120
	global_load_dwordx4 v[46:49], v[54:55], off offset:1136
	global_load_dwordx4 v[50:53], v[54:55], off offset:1152
	s_nop 0
	global_load_dwordx4 v[54:57], v[54:55], off offset:1168
	s_mov_b32 s21, s19
	s_waitcnt lgkmcnt(0)
	v_lshl_add_u64 v[58:59], v[232:233], 0, s[20:21]
	v_lshl_add_u64 v[60:61], v[16:17], 2, v[250:251]
	global_load_dword v68, v[60:61], off offset:1024
	v_lshl_add_u64 v[58:59], v[130:131], 2, v[58:59]
	v_add_co_u32_e32 v60, vcc, s28, v58
	v_add_co_u32_e64 v62, s[16:17], s30, v58
	s_nop 0
	v_addc_co_u32_e32 v61, vcc, 0, v59, vcc
	v_addc_co_u32_e64 v63, s[16:17], 0, v59, s[16:17]
	v_add_co_u32_e64 v64, s[16:17], s31, v58
	v_add_co_u32_e32 v58, vcc, s29, v58
	s_nop 0
	v_addc_co_u32_e64 v65, s[16:17], 0, v59, s[16:17]
	v_addc_co_u32_e32 v59, vcc, 0, v59, vcc
	global_load_dword v69, v[58:59], off offset:-4096
	global_load_dword v70, v[60:61], off offset:1024
	global_load_dword v71, v[60:61], off offset:2048
	s_nop 0
	global_load_dword v60, v[60:61], off offset:3072
	s_nop 0
	global_load_dword v61, v[58:59], off
	global_load_dword v72, v[58:59], off offset:1024
	global_load_dword v73, v[58:59], off offset:2048
	s_nop 0
	global_load_dword v58, v[58:59], off offset:3072
	s_nop 0
	global_load_dword v59, v[64:65], off offset:-4096
	global_load_dword v74, v[62:63], off offset:1024
	global_load_dword v75, v[62:63], off offset:2048
	s_nop 0
	global_load_dword v62, v[62:63], off offset:3072
	s_nop 0
	global_load_dword v63, v[64:65], off
	global_load_dword v76, v[64:65], off offset:1024
	global_load_dword v77, v[64:65], off offset:2048
	s_nop 0
	global_load_dword v64, v[64:65], off offset:3072
	global_load_dwordx4 v[234:237], v[234:235], off
	global_load_dwordx4 v[238:241], v[238:239], off
	global_load_dwordx4 v[242:245], v[242:243], off
	global_load_dwordx4 v[246:249], v[246:247], off
	v_cmp_lt_i32_e32 vcc, v36, v35
	s_waitcnt vmcnt(4)
	v_mul_f32_e32 v66, 0x3e000000, v66
	v_mul_f32_e32 v78, v66, v67
	v_cndmask_b32_e32 v65, v1, v36, vcc
	v_lshlrev_b32_e32 v65, 2, v65
	ds_bpermute_b32 v65, v65, v78
	v_cmp_lt_i32_e32 vcc, v37, v35
	s_waitcnt lgkmcnt(0)
	v_fmac_f32_e32 v65, v66, v67
	v_cndmask_b32_e32 v78, v1, v37, vcc
	v_lshlrev_b32_e32 v78, 2, v78
	ds_bpermute_b32 v78, v78, v65
	v_cmp_lt_i32_e32 vcc, v38, v35
	s_waitcnt lgkmcnt(0)
	v_add_f32_e32 v65, v65, v78
	v_cndmask_b32_e32 v79, v1, v38, vcc
	v_cmp_lt_i32_e32 vcc, v39, v35
	v_lshlrev_b32_e32 v79, 2, v79
	ds_bpermute_b32 v78, v79, v65
	v_cndmask_b32_e32 v80, v1, v39, vcc
	v_cmp_lt_i32_e32 vcc, v40, v35
	v_lshlrev_b32_e32 v80, 2, v80
	s_waitcnt lgkmcnt(0)
	v_add_f32_e32 v65, v65, v78
	v_cndmask_b32_e32 v79, v1, v40, vcc
	v_cmp_lt_i32_e32 vcc, v41, v35
	ds_bpermute_b32 v78, v80, v65
	v_fmac_f32_e32 v68, v42, v69
	v_fmac_f32_e32 v68, v43, v70
	v_fmac_f32_e32 v68, v44, v71
	v_fmac_f32_e32 v68, v45, v60
	v_fmac_f32_e32 v68, v46, v61
	v_fmac_f32_e32 v68, v47, v72
	v_fmac_f32_e32 v68, v48, v73
	v_fmac_f32_e32 v68, v49, v58
	v_fmac_f32_e32 v68, v50, v59
	v_fmac_f32_e32 v68, v51, v74
	v_fmac_f32_e32 v68, v52, v75
	v_fmac_f32_e32 v68, v53, v62
	v_fmac_f32_e32 v68, v54, v63
	v_fmac_f32_e32 v68, v55, v76
	v_fmac_f32_e32 v68, v56, v77
	v_fmac_f32_e32 v68, v57, v64
	v_mul_f32_e64 v42, |v68|, s33
	v_exp_f32_e32 v42, v42
	v_cndmask_b32_e32 v81, v1, v41, vcc
	v_lshlrev_b32_e32 v43, 2, v79
	s_waitcnt lgkmcnt(0)
	v_add_f32_e32 v45, v65, v78
	v_add_f32_e32 v42, 1.0, v42
	v_cmp_gt_f32_e32 vcc, s34, v42
	ds_bpermute_b32 v43, v43, v45
	v_lshlrev_b32_e32 v44, 2, v81
	v_cndmask_b32_e64 v46, 0, 32, vcc
	v_ldexp_f32 v42, v42, v46
	v_log_f32_e32 v42, v42
	v_cndmask_b32_e32 v47, 0, v34, vcc
	v_min_f32_e32 v46, 0, v68
	v_mul_f32_e32 v48, 0x3f317217, v42
	v_fma_f32 v48, v42, s35, -v48
	v_fmac_f32_e32 v48, 0x3377d1cf, v42
	v_fmac_f32_e32 v48, 0x3f317217, v42
	v_cmp_lt_f32_e64 vcc, |v42|, s36
	s_nop 1
	v_cndmask_b32_e32 v42, v42, v48, vcc
	v_sub_f32_e32 v42, v42, v47
	v_sub_f32_e32 v42, v46, v42
	v_mul_f32_e32 v42, 0x3d800000, v42
	v_mul_f32_e32 v42, 0x3fb8aa3b, v42
	v_exp_f32_e32 v46, v42
	s_waitcnt lgkmcnt(0)
	v_add_f32_e32 v42, v45, v43
	ds_bpermute_b32 v43, v44, v42
	v_mul_f32_e32 v44, v66, v46
	ds_write2st64_b32 v6, v44, v67 offset0:128 offset1:129
	ds_write_b32 v6, v46 offset:33280
	s_and_saveexec_b64 s[16:17], s[12:13]
	s_cbranch_execz .LBB0_4254
	s_waitcnt lgkmcnt(2)
	v_add_f32_e32 v42, v42, v43
	v_mov_b32_e32 v43, s94
	ds_write_b32 v43, v42 offset:34048

.LBB0_4255:
	s_or_b64 exec, exec, s[24:25]
	s_waitcnt lgkmcnt(0)
	v_mov_b64_e32 v[42:43], s[0:1]
	s_waitcnt lgkmcnt(0)
	s_barrier
	s_and_b32 s16, s2, 0x7ffffffc
	s_mov_b32 s17, s19
	s_add_i32 s16, s3, s16
	s_lshl_b64 s[16:17], s[16:17], 15
	s_add_u32 s16, s4, s16
	s_addc_u32 s17, s5, s17
	v_lshl_add_u64 v[54:55], s[16:17], 0, v[18:19]
	v_lshl_add_u64 v[62:63], s[16:17], 0, v[20:21]
	v_lshl_add_u64 v[64:65], s[16:17], 0, v[22:23]
	v_lshl_add_u64 v[66:67], s[16:17], 0, v[24:25]
	ds_read_b128 v[46:49], v3 offset:33536
	ds_read2st64_b32 v[52:53], v26 offset0:129 offset1:130
	ds_read2st64_b32 v[56:57], v27 offset0:129 offset1:130
	ds_read2st64_b32 v[58:59], v28 offset0:129 offset1:130
	ds_read2st64_b32 v[60:61], v29 offset0:129 offset1:130
	s_waitcnt vmcnt(0)
	ds_write_b128 v2, v[234:237]
	ds_write_b128 v7, v[238:241]
	ds_write_b128 v30, v[242:245]
	ds_write_b128 v31, v[246:249]
	s_waitcnt lgkmcnt(4)
	v_pk_mul_f32 v[44:45], v[48:49], v[52:53] op_sel_hi:[1,0]
	v_pk_mul_f32 v[42:43], v[46:47], v[52:53] op_sel_hi:[1,0]
	v_mov_b32_e32 v52, v53
	v_pk_fma_f32 v[236:237], v[236:237], v[52:53], v[44:45] op_sel_hi:[1,0,1]
	v_pk_fma_f32 v[234:235], v[234:235], v[52:53], v[42:43] op_sel_hi:[1,0,1]
	global_store_dwordx4 v[54:55], v[234:237], off
	v_pk_mul_f32 v[44:45], v[48:49], v[56:57] op_sel_hi:[1,0]
	v_pk_mul_f32 v[42:43], v[46:47], v[56:57] op_sel_hi:[1,0]
	v_mov_b32_e32 v56, v57
	v_pk_fma_f32 v[240:241], v[240:241], v[56:57], v[44:45] op_sel_hi:[1,0,1]
	v_pk_fma_f32 v[238:239], v[238:239], v[56:57], v[42:43] op_sel_hi:[1,0,1]
	global_store_dwordx4 v[62:63], v[238:241], off
	v_pk_mul_f32 v[44:45], v[48:49], v[58:59] op_sel_hi:[1,0]
	v_pk_mul_f32 v[42:43], v[46:47], v[58:59] op_sel_hi:[1,0]
	v_mov_b32_e32 v58, v59
	v_pk_fma_f32 v[244:245], v[244:245], v[58:59], v[44:45] op_sel_hi:[1,0,1]
	v_pk_fma_f32 v[242:243], v[242:243], v[58:59], v[42:43] op_sel_hi:[1,0,1]
	global_store_dwordx4 v[64:65], v[242:245], off
	v_pk_mul_f32 v[44:45], v[48:49], v[60:61] op_sel_hi:[1,0]
	v_pk_mul_f32 v[42:43], v[46:47], v[60:61] op_sel_hi:[1,0]
	v_mov_b32_e32 v60, v61
	v_pk_fma_f32 v[248:249], v[248:249], v[60:61], v[44:45] op_sel_hi:[1,0,1]
	v_pk_fma_f32 v[246:247], v[246:247], v[60:61], v[42:43] op_sel_hi:[1,0,1]
	global_store_dwordx4 v[66:67], v[246:249], off
	s_waitcnt lgkmcnt(0)
	s_barrier
	v_mov_b32_e32 v42, 0
	s_and_saveexec_b64 s[16:17], s[8:9]
	s_cbranch_execz .LBB0_4261
	v_lshl_add_u64 v[44:45], v[12:13], 2, s[22:23]
	global_load_dword v234, v[44:45], off
	v_lshl_add_u64 v[44:45], v[130:131], 2, v[252:253]
	global_load_dword v235, v[44:45], off offset:512
	v_mov_b32_e32 v42, 0
	s_mov_b32 s21, 0
	s_mov_b32 s24, s27

.LBB0_4261:
	s_or_b64 exec, exec, s[16:17]
	s_waitcnt lgkmcnt(0)
	s_barrier
	s_and_saveexec_b64 s[24:25], s[8:9]
	s_cbranch_execz .LBB0_4246
	v_mov_b32_e32 v43, s37
	ds_read2_b32 v[44:45], v43 offset1:1
	s_waitcnt lgkmcnt(0)
	v_add_f32_e32 v44, v44, v45
	v_fmamk_f32 v44, v44, 0x3c000000, v32
	v_mul_f32_e32 v45, 0x4f800000, v44
	v_cmp_gt_f32_e32 vcc, s41, v44
	v_cndmask_b32_e32 v44, v44, v45, vcc
	v_sqrt_f32_e32 v45, v44
	s_nop 0
	v_add_u32_e32 v47, -1, v45
	v_add_u32_e32 v48, 1, v45
	v_fma_f32 v49, -v47, v45, v44
	v_fma_f32 v50, -v48, v45, v44
	v_cmp_ge_f32_e64 s[16:17], 0, v49
	s_nop 1
	v_cndmask_b32_e64 v45, v45, v47, s[16:17]
	v_cmp_lt_f32_e64 s[16:17], 0, v50
	s_nop 1
	v_cndmask_b32_e64 v45, v45, v48, s[16:17]
	v_mul_f32_e32 v47, 0x37800000, v45
	v_cndmask_b32_e32 v45, v45, v47, vcc
	v_cmp_class_f32_e32 vcc, v44, v33
	s_nop 1
	v_cndmask_b32_e32 v44, v45, v44, vcc
	v_div_scale_f32 v45, s[16:17], v44, v44, 1.0
	v_rcp_f32_e32 v47, v45
	v_div_scale_f32 v48, vcc, 1.0, v44, 1.0
	s_lshl_b64 s[16:17], s[18:19], 11
	v_fma_f32 v49, -v45, v47, 1.0
	v_fmac_f32_e32 v47, v49, v47
	v_mul_f32_e32 v49, v48, v47
	v_fma_f32 v50, -v45, v49, v48
	v_fmac_f32_e32 v49, v50, v47
	v_fma_f32 v45, -v45, v49, v48
	s_waitcnt vmcnt(0)
	v_mov_b32_e32 v43, v234
	v_mov_b32_e32 v46, v235
	v_mul_f32_e32 v48, 0xbfb8aa3b, v43
	v_exp_f32_e32 v48, v48
	v_div_fmas_f32 v45, v45, v47, v49
	v_div_fixup_f32 v44, v45, v44, 1.0
	v_mul_f32_e32 v42, v42, v44
	v_add_f32_e32 v45, 1.0, v48
	v_div_scale_f32 v47, s[22:23], v45, v45, v43
	v_rcp_f32_e32 v48, v47
	v_div_scale_f32 v44, vcc, v43, v45, v43
	v_fma_f32 v49, -v47, v48, 1.0
	v_fmac_f32_e32 v48, v49, v48
	v_mul_f32_e32 v49, v44, v48
	v_fma_f32 v50, -v47, v49, v44
	v_fmac_f32_e32 v49, v50, v48
	v_fma_f32 v44, -v47, v49, v44
	v_div_fmas_f32 v44, v44, v48, v49
	v_div_fixup_f32 v43, v44, v45, v43
	v_mul_f32_e32 v42, v46, v42
	v_mul_f32_e32 v42, v42, v43
	v_bfe_u32 v43, v42, 16, 1
	v_add3_u32 v44, v42, v43, s42
	v_lshl_add_u64 v[42:43], v[14:15], 0, s[16:17]
	global_store_short_d16_hi v[42:43], v44, off
	s_branch .LBB0_4246
